# P2 bf16 K-loop: all LDS-DMA staging issued from the MFMA segments (stacked on the P8 change)
# speedup vs baseline: 1.0043x; 1.0043x over previous
.LBB0_290:
	ds_read_b128 v[154:157], v150
	ds_read_b128 v[158:161], v150 offset:1024
	ds_read_b128 v[162:165], v150 offset:2048
	ds_read_b128 v[166:169], v150 offset:3072
	ds_read_b128 v[170:173], v151
	ds_read_b128 v[174:177], v151 offset:1024
	ds_read_b128 v[178:181], v151 offset:2048
	ds_read_b128 v[182:185], v151 offset:3072
	s_add_u32 s44, s50, 0xfff00080
	s_addc_u32 s45, s51, -1
	s_cmp_eq_u32 s74, 60
	s_cselect_b32 s55, s37, s45
	s_cselect_b32 s54, s70, s44
	s_cselect_b32 s53, s27, s73
	s_cselect_b32 s52, s71, s72
	s_add_u32 s94, s50, 0xfff00000
	s_addc_u32 s95, s51, -1
	ds_read_b128 v[186:189], v152
	ds_read_b128 v[190:193], v152 offset:1024
	ds_read_b128 v[194:197], v152 offset:2048
	ds_read_b128 v[198:201], v152 offset:3072
	ds_read_b128 v[202:205], v152 offset:4096
	ds_read_b128 v[206:209], v152 offset:5120
	ds_read_b128 v[210:213], v152 offset:6144
	ds_read_b128 v[214:217], v152 offset:7168
	v_lshl_add_u64 v[226:227], s[94:95], 0, v[138:139]
	v_lshl_add_u64 v[228:229], s[94:95], 0, v[140:141]
	v_lshl_add_u64 v[230:231], s[50:51], 0, v[138:139]
	v_lshl_add_u64 v[232:233], s[50:51], 0, v[140:141]
	s_waitcnt vmcnt(4)
	s_waitcnt lgkmcnt(0)
	s_barrier
	s_setprio 1
	s_waitcnt lgkmcnt(0)
	v_mfma_f32_16x16x32_bf16 v[126:129], v[154:157], v[186:189], v[126:129]
	s_mov_b32 m0, s61
	s_nop 0
	global_load_lds_dwordx4 v[226:227], off
	v_mfma_f32_16x16x32_bf16 v[122:125], v[162:165], v[186:189], v[122:125]
	v_mfma_f32_16x16x32_bf16 v[118:121], v[154:157], v[194:197], v[118:121]
	v_mfma_f32_16x16x32_bf16 v[110:113], v[162:165], v[194:197], v[110:113]
	v_mfma_f32_16x16x32_bf16 v[102:105], v[154:157], v[202:205], v[102:105]
	v_mfma_f32_16x16x32_bf16 v[94:97], v[162:165], v[202:205], v[94:97]
	v_mfma_f32_16x16x32_bf16 v[86:89], v[154:157], v[210:213], v[86:89]
	v_mfma_f32_16x16x32_bf16 v[78:81], v[162:165], v[210:213], v[78:81]
	v_mfma_f32_16x16x32_bf16 v[126:129], v[158:161], v[190:193], v[126:129]
	s_mov_b32 m0, s62
	s_nop 0
	global_load_lds_dwordx4 v[228:229], off
	v_mfma_f32_16x16x32_bf16 v[122:125], v[166:169], v[190:193], v[122:125]
	v_mfma_f32_16x16x32_bf16 v[118:121], v[158:161], v[198:201], v[118:121]
	v_mfma_f32_16x16x32_bf16 v[110:113], v[166:169], v[198:201], v[110:113]
	v_mfma_f32_16x16x32_bf16 v[102:105], v[158:161], v[206:209], v[102:105]
	v_mfma_f32_16x16x32_bf16 v[94:97], v[166:169], v[206:209], v[94:97]
	v_mfma_f32_16x16x32_bf16 v[86:89], v[158:161], v[214:217], v[86:89]
	v_mfma_f32_16x16x32_bf16 v[78:81], v[166:169], v[214:217], v[78:81]
	s_setprio 0
	s_setprio 1
	v_mfma_f32_16x16x32_bf16 v[114:117], v[170:173], v[186:189], v[114:117]
	s_add_i32 m0, s43, 0xc000
	s_nop 0
	global_load_lds_dwordx4 v[230:231], off
	v_mfma_f32_16x16x32_bf16 v[106:109], v[178:181], v[186:189], v[106:109]
	v_mfma_f32_16x16x32_bf16 v[98:101], v[170:173], v[194:197], v[98:101]
	v_mfma_f32_16x16x32_bf16 v[90:93], v[178:181], v[194:197], v[90:93]
	v_mfma_f32_16x16x32_bf16 v[82:85], v[170:173], v[202:205], v[82:85]
	v_mfma_f32_16x16x32_bf16 v[74:77], v[178:181], v[202:205], v[74:77]
	v_mfma_f32_16x16x32_bf16 v[70:73], v[170:173], v[210:213], v[70:73]
	v_mfma_f32_16x16x32_bf16 v[66:69], v[178:181], v[210:213], v[66:69]
	v_mfma_f32_16x16x32_bf16 v[114:117], v[174:177], v[190:193], v[114:117]
	s_add_i32 m0, s43, 0xe000
	s_nop 0
	global_load_lds_dwordx4 v[232:233], off
	v_mfma_f32_16x16x32_bf16 v[106:109], v[182:185], v[190:193], v[106:109]
	v_mfma_f32_16x16x32_bf16 v[98:101], v[174:177], v[198:201], v[98:101]
	v_mfma_f32_16x16x32_bf16 v[90:93], v[182:185], v[198:201], v[90:93]
	v_mfma_f32_16x16x32_bf16 v[82:85], v[174:177], v[206:209], v[82:85]
	v_mfma_f32_16x16x32_bf16 v[74:77], v[182:185], v[206:209], v[74:77]
	v_mfma_f32_16x16x32_bf16 v[70:73], v[174:177], v[214:217], v[70:73]
	v_mfma_f32_16x16x32_bf16 v[66:69], v[182:185], v[214:217], v[66:69]
	s_setprio 0
	s_barrier
	s_add_u32 s76, s52, 0x100000
	s_addc_u32 s77, s53, 0
	ds_read_b128 v[186:189], v152 offset:16384
	ds_read_b128 v[190:193], v152 offset:17408
	ds_read_b128 v[194:197], v152 offset:18432
	ds_read_b128 v[198:201], v152 offset:19456
	ds_read_b128 v[202:205], v152 offset:20480
	ds_read_b128 v[206:209], v152 offset:21504
	ds_read_b128 v[210:213], v152 offset:22528
	ds_read_b128 v[214:217], v152 offset:23552
	v_lshl_add_u64 v[146:147], s[52:53], 0, v[134:135]
	v_lshl_add_u64 v[218:219], s[52:53], 0, v[130:131]
	v_lshl_add_u64 v[220:221], s[54:55], 0, v[136:137]
	v_lshl_add_u64 v[222:223], s[54:55], 0, v[132:133]
	v_lshl_add_u64 v[226:227], s[76:77], 0, v[134:135]
	v_lshl_add_u64 v[228:229], s[76:77], 0, v[130:131]
	s_waitcnt vmcnt(2)
	s_waitcnt lgkmcnt(0)
	s_barrier
	s_setprio 1
	s_waitcnt lgkmcnt(0)
	v_mfma_f32_16x16x32_bf16 v[62:65], v[154:157], v[186:189], v[62:65]
	s_add_i32 m0, s63, s49
	s_nop 0
	global_load_lds_dwordx4 v[146:147], off
	v_mfma_f32_16x16x32_bf16 v[58:61], v[162:165], v[186:189], v[58:61]
	v_mfma_f32_16x16x32_bf16 v[54:57], v[154:157], v[194:197], v[54:57]
	v_mfma_f32_16x16x32_bf16 v[46:49], v[162:165], v[194:197], v[46:49]
	v_mfma_f32_16x16x32_bf16 v[38:41], v[154:157], v[202:205], v[38:41]
	v_mfma_f32_16x16x32_bf16 v[30:33], v[162:165], v[202:205], v[30:33]
	v_mfma_f32_16x16x32_bf16 v[22:25], v[154:157], v[210:213], v[22:25]
	v_mfma_f32_16x16x32_bf16 v[14:17], v[162:165], v[210:213], v[14:17]
	v_mfma_f32_16x16x32_bf16 v[62:65], v[158:161], v[190:193], v[62:65]
	s_add_i32 s94, s63, s49
	s_add_i32 m0, s94, 0x2000
	s_nop 0
	global_load_lds_dwordx4 v[218:219], off
	v_mfma_f32_16x16x32_bf16 v[58:61], v[166:169], v[190:193], v[58:61]
	v_mfma_f32_16x16x32_bf16 v[54:57], v[158:161], v[198:201], v[54:57]
	v_mfma_f32_16x16x32_bf16 v[46:49], v[166:169], v[198:201], v[46:49]
	v_mfma_f32_16x16x32_bf16 v[38:41], v[158:161], v[206:209], v[38:41]
	v_mfma_f32_16x16x32_bf16 v[30:33], v[166:169], v[206:209], v[30:33]
	v_mfma_f32_16x16x32_bf16 v[22:25], v[158:161], v[214:217], v[22:25]
	v_mfma_f32_16x16x32_bf16 v[14:17], v[166:169], v[214:217], v[14:17]
	s_setprio 0
	s_setprio 1
	v_mfma_f32_16x16x32_bf16 v[50:53], v[170:173], v[186:189], v[50:53]
	s_add_i32 m0, s64, s49
	s_nop 0
	global_load_lds_dwordx4 v[226:227], off
	v_mfma_f32_16x16x32_bf16 v[42:45], v[178:181], v[186:189], v[42:45]
	v_mfma_f32_16x16x32_bf16 v[34:37], v[170:173], v[194:197], v[34:37]
	v_mfma_f32_16x16x32_bf16 v[26:29], v[178:181], v[194:197], v[26:29]
	v_mfma_f32_16x16x32_bf16 v[18:21], v[170:173], v[202:205], v[18:21]
	v_mfma_f32_16x16x32_bf16 v[10:13], v[178:181], v[202:205], v[10:13]
	v_mfma_f32_16x16x32_bf16 v[6:9], v[170:173], v[210:213], v[6:9]
	v_mfma_f32_16x16x32_bf16 v[2:5], v[178:181], v[210:213], v[2:5]
	v_mfma_f32_16x16x32_bf16 v[50:53], v[174:177], v[190:193], v[50:53]
	s_add_i32 s94, s64, s49
	s_add_i32 m0, s94, 0x2000
	s_nop 0
	global_load_lds_dwordx4 v[228:229], off
	v_mfma_f32_16x16x32_bf16 v[42:45], v[182:185], v[190:193], v[42:45]
	v_mfma_f32_16x16x32_bf16 v[34:37], v[174:177], v[198:201], v[34:37]
	v_mfma_f32_16x16x32_bf16 v[26:29], v[182:185], v[198:201], v[26:29]
	v_mfma_f32_16x16x32_bf16 v[18:21], v[174:177], v[206:209], v[18:21]
	v_mfma_f32_16x16x32_bf16 v[10:13], v[182:185], v[206:209], v[10:13]
	v_mfma_f32_16x16x32_bf16 v[6:9], v[174:177], v[214:217], v[6:9]
	v_mfma_f32_16x16x32_bf16 v[2:5], v[182:185], v[214:217], v[2:5]
	s_setprio 0
	s_barrier
	s_add_i32 s44, 0, 0x18000
	v_add_u32_e32 v153, s44, v148
	s_add_i32 s45, 0, 0x1c000
	ds_read_b128 v[154:157], v153
	ds_read_b128 v[158:161], v153 offset:1024
	ds_read_b128 v[162:165], v153 offset:2048
	ds_read_b128 v[166:169], v153 offset:3072
	v_add_u32_e32 v153, s45, v148
	ds_read_b128 v[170:173], v153
	ds_read_b128 v[174:177], v153 offset:1024
	ds_read_b128 v[178:181], v153 offset:2048
	ds_read_b128 v[182:185], v153 offset:3072
	s_add_u32 s54, s54, 0x100000
	s_addc_u32 s55, s55, 0
	ds_read_b128 v[186:189], v152 offset:32768
	ds_read_b128 v[190:193], v152 offset:33792
	ds_read_b128 v[194:197], v152 offset:34816
	ds_read_b128 v[198:201], v152 offset:35840
	ds_read_b128 v[202:205], v152 offset:36864
	ds_read_b128 v[206:209], v152 offset:37888
	ds_read_b128 v[210:213], v152 offset:38912
	ds_read_b128 v[214:217], v152 offset:39936
	v_lshl_add_u64 v[226:227], s[54:55], 0, v[136:137]
	v_lshl_add_u64 v[228:229], s[54:55], 0, v[132:133]
	s_waitcnt vmcnt(4)
	s_waitcnt lgkmcnt(0)
	s_barrier
	s_setprio 1
	s_waitcnt lgkmcnt(0)
	v_mfma_f32_16x16x32_bf16 v[126:129], v[154:157], v[186:189], v[126:129]
	s_mov_b32 m0, s43
	s_nop 0
	global_load_lds_dwordx4 v[220:221], off
	v_mfma_f32_16x16x32_bf16 v[122:125], v[162:165], v[186:189], v[122:125]
	v_mfma_f32_16x16x32_bf16 v[118:121], v[154:157], v[194:197], v[118:121]
	v_mfma_f32_16x16x32_bf16 v[110:113], v[162:165], v[194:197], v[110:113]
	v_mfma_f32_16x16x32_bf16 v[102:105], v[154:157], v[202:205], v[102:105]
	v_mfma_f32_16x16x32_bf16 v[94:97], v[162:165], v[202:205], v[94:97]
	v_mfma_f32_16x16x32_bf16 v[86:89], v[154:157], v[210:213], v[86:89]
	v_mfma_f32_16x16x32_bf16 v[78:81], v[162:165], v[210:213], v[78:81]
	v_mfma_f32_16x16x32_bf16 v[126:129], v[158:161], v[190:193], v[126:129]
	s_mov_b32 m0, s57
	s_nop 0
	global_load_lds_dwordx4 v[222:223], off
	v_mfma_f32_16x16x32_bf16 v[122:125], v[166:169], v[190:193], v[122:125]
	v_mfma_f32_16x16x32_bf16 v[118:121], v[158:161], v[198:201], v[118:121]
	v_mfma_f32_16x16x32_bf16 v[110:113], v[166:169], v[198:201], v[110:113]
	v_mfma_f32_16x16x32_bf16 v[102:105], v[158:161], v[206:209], v[102:105]
	v_mfma_f32_16x16x32_bf16 v[94:97], v[166:169], v[206:209], v[94:97]
	v_mfma_f32_16x16x32_bf16 v[86:89], v[158:161], v[214:217], v[86:89]
	v_mfma_f32_16x16x32_bf16 v[78:81], v[166:169], v[214:217], v[78:81]
	s_setprio 0
	s_setprio 1
	v_mfma_f32_16x16x32_bf16 v[114:117], v[170:173], v[186:189], v[114:117]
	s_mov_b32 m0, s58
	s_nop 0
	global_load_lds_dwordx4 v[226:227], off
	v_mfma_f32_16x16x32_bf16 v[106:109], v[178:181], v[186:189], v[106:109]
	v_mfma_f32_16x16x32_bf16 v[98:101], v[170:173], v[194:197], v[98:101]
	v_mfma_f32_16x16x32_bf16 v[90:93], v[178:181], v[194:197], v[90:93]
	v_mfma_f32_16x16x32_bf16 v[82:85], v[170:173], v[202:205], v[82:85]
	v_mfma_f32_16x16x32_bf16 v[74:77], v[178:181], v[202:205], v[74:77]
	v_mfma_f32_16x16x32_bf16 v[70:73], v[170:173], v[210:213], v[70:73]
	v_mfma_f32_16x16x32_bf16 v[66:69], v[178:181], v[210:213], v[66:69]
	v_mfma_f32_16x16x32_bf16 v[114:117], v[174:177], v[190:193], v[114:117]
	s_mov_b32 m0, s59
	s_nop 0
	global_load_lds_dwordx4 v[228:229], off
	v_mfma_f32_16x16x32_bf16 v[106:109], v[182:185], v[190:193], v[106:109]
	v_mfma_f32_16x16x32_bf16 v[98:101], v[174:177], v[198:201], v[98:101]
	v_mfma_f32_16x16x32_bf16 v[90:93], v[182:185], v[198:201], v[90:93]
	v_mfma_f32_16x16x32_bf16 v[82:85], v[174:177], v[206:209], v[82:85]
	v_mfma_f32_16x16x32_bf16 v[74:77], v[182:185], v[206:209], v[74:77]
	v_mfma_f32_16x16x32_bf16 v[70:73], v[174:177], v[214:217], v[70:73]
	v_mfma_f32_16x16x32_bf16 v[66:69], v[182:185], v[214:217], v[66:69]
	s_setprio 0
	s_barrier
	s_add_u32 s52, s52, 0x100080
	s_addc_u32 s53, s53, 0
	ds_read_b128 v[186:189], v152 offset:49152
	ds_read_b128 v[190:193], v152 offset:50176
	ds_read_b128 v[194:197], v152 offset:51200
	ds_read_b128 v[198:201], v152 offset:52224
	ds_read_b128 v[202:205], v152 offset:53248
	ds_read_b128 v[206:209], v152 offset:54272
	ds_read_b128 v[210:213], v152 offset:55296
	ds_read_b128 v[214:217], v152 offset:56320
	v_lshl_add_u64 v[226:227], v[146:147], 0, s[14:15]
	v_lshl_add_u64 v[228:229], v[218:219], 0, s[14:15]
	v_lshl_add_u64 v[230:231], s[52:53], 0, v[134:135]
	v_lshl_add_u64 v[232:233], s[52:53], 0, v[130:131]
	s_waitcnt vmcnt(2)
	s_waitcnt lgkmcnt(0)
	s_barrier
	s_setprio 1
	s_waitcnt lgkmcnt(0)
	v_mfma_f32_16x16x32_bf16 v[62:65], v[154:157], v[186:189], v[62:65]
	s_add_i32 m0, s49, 0x18000
	s_nop 0
	global_load_lds_dwordx4 v[226:227], off
	v_mfma_f32_16x16x32_bf16 v[58:61], v[162:165], v[186:189], v[58:61]
	v_mfma_f32_16x16x32_bf16 v[54:57], v[154:157], v[194:197], v[54:57]
	v_mfma_f32_16x16x32_bf16 v[46:49], v[162:165], v[194:197], v[46:49]
	v_mfma_f32_16x16x32_bf16 v[38:41], v[154:157], v[202:205], v[38:41]
	v_mfma_f32_16x16x32_bf16 v[30:33], v[162:165], v[202:205], v[30:33]
	v_mfma_f32_16x16x32_bf16 v[22:25], v[154:157], v[210:213], v[22:25]
	v_mfma_f32_16x16x32_bf16 v[14:17], v[162:165], v[210:213], v[14:17]
	v_mfma_f32_16x16x32_bf16 v[62:65], v[158:161], v[190:193], v[62:65]
	s_add_i32 m0, s49, 0x1a000
	s_nop 0
	global_load_lds_dwordx4 v[228:229], off
	v_mfma_f32_16x16x32_bf16 v[58:61], v[166:169], v[190:193], v[58:61]
	v_mfma_f32_16x16x32_bf16 v[54:57], v[158:161], v[198:201], v[54:57]
	v_mfma_f32_16x16x32_bf16 v[46:49], v[166:169], v[198:201], v[46:49]
	v_mfma_f32_16x16x32_bf16 v[38:41], v[158:161], v[206:209], v[38:41]
	v_mfma_f32_16x16x32_bf16 v[30:33], v[166:169], v[206:209], v[30:33]
	v_mfma_f32_16x16x32_bf16 v[22:25], v[158:161], v[214:217], v[22:25]
	v_mfma_f32_16x16x32_bf16 v[14:17], v[166:169], v[214:217], v[14:17]
	s_setprio 0
	s_setprio 1
	v_mfma_f32_16x16x32_bf16 v[50:53], v[170:173], v[186:189], v[50:53]
	s_add_i32 m0, s49, 0x1c000
	s_nop 0
	global_load_lds_dwordx4 v[230:231], off
	v_mfma_f32_16x16x32_bf16 v[42:45], v[178:181], v[186:189], v[42:45]
	v_mfma_f32_16x16x32_bf16 v[34:37], v[170:173], v[194:197], v[34:37]
	v_mfma_f32_16x16x32_bf16 v[26:29], v[178:181], v[194:197], v[26:29]
	v_mfma_f32_16x16x32_bf16 v[18:21], v[170:173], v[202:205], v[18:21]
	v_mfma_f32_16x16x32_bf16 v[10:13], v[178:181], v[202:205], v[10:13]
	v_mfma_f32_16x16x32_bf16 v[6:9], v[170:173], v[210:213], v[6:9]
	v_mfma_f32_16x16x32_bf16 v[2:5], v[178:181], v[210:213], v[2:5]
	v_mfma_f32_16x16x32_bf16 v[50:53], v[174:177], v[190:193], v[50:53]
	s_add_i32 m0, s49, 0x1e000
	s_nop 0
	global_load_lds_dwordx4 v[232:233], off
	v_mfma_f32_16x16x32_bf16 v[42:45], v[182:185], v[190:193], v[42:45]
	v_mfma_f32_16x16x32_bf16 v[34:37], v[174:177], v[198:201], v[34:37]
	v_mfma_f32_16x16x32_bf16 v[26:29], v[182:185], v[198:201], v[26:29]
	v_mfma_f32_16x16x32_bf16 v[18:21], v[174:177], v[206:209], v[18:21]
	v_mfma_f32_16x16x32_bf16 v[10:13], v[182:185], v[206:209], v[10:13]
	v_mfma_f32_16x16x32_bf16 v[6:9], v[174:177], v[214:217], v[6:9]
	v_mfma_f32_16x16x32_bf16 v[2:5], v[182:185], v[214:217], v[2:5]
	s_setprio 0
	s_barrier
	s_add_i32 s74, s74, 2
	s_add_u32 s50, s50, 0x100
	s_addc_u32 s51, s51, 0
	s_add_u32 s72, s72, 0x100
	s_addc_u32 s73, s73, 0
	s_cmp_lt_u32 s74, 62
	s_cbranch_scc1 .LBB0_290
	s_andn2_b64 vcc, exec, s[16:17]
	s_cbranch_vccnz .LBB0_293
	s_barrier
